# stage-level s_setprio 2 for waves 4-7 over the whole scan MFMA stage (instead of loop-level)
# baseline (speedup 1.0000x reference)
.LBB0_780:
	v_mov_b32_e32 v16, v155
	s_setprio 0
	s_waitcnt lgkmcnt(0)
	s_barrier
	s_xor_b64 s[52:53], s[52:53], -1
	v_lshrrev_b32_e32 v17, 3, v16
	v_and_b32_e32 v17, 0xffffffc, v17
	v_add_u32_e32 v17, s22, v17
	v_lshlrev_b32_e32 v16, 1, v16
	v_and_b32_e32 v16, 62, v16
	v_mul_lo_u32 v17, v17, s20
	v_add3_u32 v16, s29, v16, v17
	v_cvt_pk_bf16_f32 v17, v1, v49
	ds_write_b16 v16, v17 offset:272
	v_cvt_pk_bf16_f32 v17, v2, v49
	ds_write_b16 v16, v17 offset:544
	v_cvt_pk_bf16_f32 v17, v3, v49
	ds_write_b16 v16, v17 offset:816
	v_cvt_pk_bf16_f32 v17, v4, v49
	ds_write_b16 v16, v17 offset:2176
	v_cvt_pk_bf16_f32 v17, v5, v49
	ds_write_b16 v16, v17 offset:2448
	v_cvt_pk_bf16_f32 v17, v6, v49
	ds_write_b16 v16, v17 offset:2720
	v_cvt_pk_bf16_f32 v17, v7, v49
	ds_write_b16 v16, v17 offset:2992
	v_cvt_pk_bf16_f32 v17, v8, v49
	ds_write_b16 v16, v17 offset:4352
	v_cvt_pk_bf16_f32 v17, v9, v49
	ds_write_b16 v16, v17 offset:4624
	v_cvt_pk_bf16_f32 v17, v10, v49
	ds_write_b16 v16, v17 offset:4896
	v_cvt_pk_bf16_f32 v17, v11, v49
	ds_write_b16 v16, v17 offset:5168
	v_cvt_pk_bf16_f32 v17, v12, v49
	ds_write_b16 v16, v17 offset:6528
	v_cvt_pk_bf16_f32 v17, v13, v49
	ds_write_b16 v16, v17 offset:6800
	v_cvt_pk_bf16_f32 v17, v14, v49
	s_cmp_lg_u32 s35, 16
	v_cvt_pk_bf16_f32 v18, v0, v49
	ds_write_b16 v16, v18
	ds_write_b16 v16, v17 offset:7072
	v_cvt_pk_bf16_f32 v17, v15, v49
	ds_write_b16 v16, v17 offset:7344
	s_cbranch_scc0 .LBB0_721

.LBB0_818:
	v_mov_b32_e32 v16, v155
	s_or_b32 s6, s37, s9
	v_and_b32_e32 v17, 31, v16
	v_lshrrev_b32_e32 v16, 3, v16
	s_add_i32 s6, s6, s27
	v_and_b32_e32 v16, 0x1ffffc, v16
	v_add_u32_e32 v16, s6, v16
	v_mul_lo_u32 v16, v16, s18
	v_or3_b32 v16, v16, v17, s28
	v_lshlrev_b32_e32 v16, 1, v16
	v_add_u32_e32 v17, 0x3000, v16
	v_add_u32_e32 v18, 0x6000, v16
	v_add_u32_e32 v19, 0x9000, v16
	v_add_u32_e32 v20, 0x18000, v16
	v_add_u32_e32 v21, 0x1b000, v16
	v_add_u32_e32 v22, 0x1e000, v16
	v_add_u32_e32 v23, 0x21000, v16
	global_load_ushort v175, v16, s[4:5]
	global_load_ushort v174, v17, s[4:5]
	global_load_ushort v173, v18, s[4:5]
	global_load_ushort v172, v19, s[4:5]
	global_load_ushort v171, v20, s[4:5]
	global_load_ushort v170, v21, s[4:5]
	global_load_ushort v169, v22, s[4:5]
	global_load_ushort v168, v23, s[4:5]
	v_add_u32_e32 v17, 0x30000, v16
	v_add_u32_e32 v18, 0x33000, v16
	v_add_u32_e32 v19, 0x36000, v16
	v_add_u32_e32 v20, 0x39000, v16
	v_add_u32_e32 v21, 0x48000, v16
	v_add_u32_e32 v22, 0x4b000, v16
	v_add_u32_e32 v23, 0x4e000, v16
	v_add_u32_e32 v16, 0x51000, v16
	global_load_ushort v167, v17, s[4:5]
	global_load_ushort v166, v18, s[4:5]
	global_load_ushort v165, v19, s[4:5]
	global_load_ushort v164, v20, s[4:5]
	global_load_ushort v163, v21, s[4:5]
	global_load_ushort v162, v22, s[4:5]
	global_load_ushort v146, v23, s[4:5]
	global_load_ushort v51, v16, s[4:5]
	v_mov_b32_e32 v17, v155
	v_mov_b32_e32 v16, s36
	s_waitcnt lgkmcnt(0)
	s_barrier
	s_cmp_lt_u32 s34, 3
	s_cbranch_scc1 .Lprio_skip
	s_setprio 2
.Lprio_skip:
	ds_read_b32 v16, v16 offset:2044
	v_and_b32_e32 v32, 31, v17
	v_or_b32_e32 v176, s27, v32
	v_mul_lo_u32 v18, v176, s20
	v_ashrrev_i32_e32 v34, 5, v17
	v_lshlrev_b32_e32 v177, 4, v34
	v_add_u32_e32 v18, 0, v18
	s_mov_b32 s7, 0x15400
	v_add3_u32 v37, v18, v177, s7
	ds_read_b128 v[112:115], v37
	s_waitcnt lgkmcnt(1)
	v_pk_mul_f32 v[14:15], v[14:15], v[16:17] op_sel_hi:[1,0]
	v_pk_mul_f32 v[12:13], v[12:13], v[16:17] op_sel_hi:[1,0]
	v_pk_mul_f32 v[10:11], v[10:11], v[16:17] op_sel_hi:[1,0]
	v_pk_mul_f32 v[8:9], v[8:9], v[16:17] op_sel_hi:[1,0]
	v_pk_mul_f32 v[6:7], v[6:7], v[16:17] op_sel_hi:[1,0]
	v_pk_mul_f32 v[4:5], v[4:5], v[16:17] op_sel_hi:[1,0]
	v_pk_mul_f32 v[2:3], v[2:3], v[16:17] op_sel_hi:[1,0]
	v_pk_mul_f32 v[0:1], v[0:1], v[16:17] op_sel_hi:[1,0]
	v_or_b32_e32 v16, s23, v32
	v_lshrrev_b32_e32 v47, 1, v17
	v_mul_lo_u32 v16, v16, s20
	v_add_u32_e32 v207, 0, v16
	v_xor_b32_e32 v16, v34, v47
	v_or_b32_e32 v33, s22, v32
	v_lshlrev_b32_e32 v16, 4, v16
	v_mad_u32_u24 v35, v33, s20, 0
	s_mov_b32 s7, 0x1dc00
	v_lshlrev_b32_e32 v36, 3, v34
	v_and_b32_e32 v16, 0xf0, v16
	v_add3_u32 v46, v35, v177, s7
	v_add_u32_e32 v210, v35, v16
	v_bitop3_b32 v16, v36, v32, s23 bitop3:0x1e
	ds_read_b128 v[116:119], v37 offset:32
	v_lshlrev_b32_e32 v20, 1, v16
	ds_read_b128 v[16:19], v46
	v_and_b32_e32 v20, 0xf0, v20
	v_add_u32_e32 v42, v207, v20
	s_waitcnt lgkmcnt(0)
	v_mfma_f32_32x32x16_bf16 v[16:31], v[112:115], v[16:19], 0
	ds_read_b128 v[38:41], v46 offset:32
	ds_read_b128 v[120:123], v37 offset:224
	v_add_u32_e32 v124, 16, v36
	v_lshrrev_b32_e32 v43, 3, v124
	v_xor_b32_e32 v43, v43, v47
	v_lshlrev_b32_e32 v43, 4, v43
	v_and_b32_e32 v43, 0xf0, v43
	v_bitop3_b32 v124, v124, v32, s23 bitop3:0x1e
	s_waitcnt lgkmcnt(1)
	v_mfma_f32_32x32x16_bf16 v[16:31], v[116:119], v[38:41], v[16:31]
	v_add_u32_e32 v125, v35, v43
	v_lshlrev_b32_e32 v124, 1, v124
	ds_read_b128 v[42:45], v42 offset:52224
	ds_read_b128 v[178:181], v125
	v_and_b32_e32 v132, 0xf0, v124
	ds_read_b128 v[124:127], v37 offset:64
	ds_read_b128 v[128:131], v46 offset:64
	v_add_u32_e32 v38, v207, v132
	v_add_u32_e32 v132, 32, v36
	v_lshrrev_b32_e32 v39, 3, v132
	v_xor_b32_e32 v39, v39, v47
	s_waitcnt lgkmcnt(0)
	v_mfma_f32_32x32x16_bf16 v[16:31], v[124:127], v[128:131], v[16:31]
	v_lshlrev_b32_e32 v39, 4, v39
	v_and_b32_e32 v39, 0xf0, v39
	v_add_u32_e32 v133, v35, v39
	ds_read_b128 v[128:131], v37 offset:96
	ds_read_b128 v[38:41], v38 offset:52224
	ds_read_b128 v[182:185], v133
	ds_read_b128 v[136:139], v46 offset:96
	v_bitop3_b32 v132, v132, v32, s23 bitop3:0x1e
	v_lshlrev_b32_e32 v132, 1, v132
	s_waitcnt lgkmcnt(0)
	v_mfma_f32_32x32x16_bf16 v[16:31], v[128:131], v[136:139], v[16:31]
	v_and_b32_e32 v186, 0xf0, v132
	ds_read_b128 v[132:135], v37 offset:128
	ds_read_b128 v[140:143], v46 offset:128
	v_add_u32_e32 v198, 48, v36
	v_lshrrev_b32_e32 v136, 3, v198
	v_xor_b32_e32 v136, v136, v47
	v_lshlrev_b32_e32 v136, 4, v136
	v_add_u32_e32 v190, v207, v186
	v_and_b32_e32 v186, 0xf0, v136
	ds_read_b128 v[136:139], v37 offset:160
	s_waitcnt lgkmcnt(1)
	v_mfma_f32_32x32x16_bf16 v[16:31], v[132:135], v[140:143], v[16:31]
	v_add_u32_e32 v140, v35, v186
	ds_read_b128 v[186:189], v46 offset:160
	ds_read_b128 v[190:193], v190 offset:52224
	ds_read_b128 v[194:197], v140
	v_bitop3_b32 v211, v198, v32, s23 bitop3:0x1e
	ds_read_b128 v[140:143], v37 offset:192
	ds_read_b128 v[198:201], v46 offset:192
	v_add_u32_e32 v218, 64, v36
	v_lshlrev_b32_e32 v37, 1, v211
	v_and_b32_e32 v37, 0xf0, v37
	s_waitcnt lgkmcnt(4)
	v_mfma_f32_32x32x16_bf16 v[16:31], v[136:139], v[186:189], v[16:31]
	v_lshrrev_b32_e32 v186, 3, v218
	v_xor_b32_e32 v186, v186, v47
	v_lshlrev_b32_e32 v186, 4, v186
	v_and_b32_e32 v211, 0xf0, v186
	v_add_u32_e32 v37, v207, v37
	s_lshl_b32 s7, s27, 2
	s_add_i32 s7, s36, s7
	s_waitcnt lgkmcnt(0)
	v_mfma_f32_32x32x16_bf16 v[16:31], v[140:143], v[198:201], v[16:31]
	ds_read_b128 v[186:189], v210
	ds_read_b128 v[198:201], v46 offset:224
	v_add_u32_e32 v46, v35, v211
	ds_read_b128 v[210:213], v37 offset:52224
	ds_read_b128 v[214:217], v46
	v_add_u32_e32 v46, 0x50, v36
	v_bitop3_b32 v37, v218, v32, s23 bitop3:0x1e
	v_lshlrev_b32_e32 v37, 1, v37
	v_and_b32_e32 v37, 0xf0, v37
	s_waitcnt lgkmcnt(3)
	v_mfma_f32_32x32x16_bf16 v[0:15], v[186:189], v[42:45], v[0:15]
	v_add_u32_e32 v37, v207, v37
	s_andn2_b64 vcc, exec, s[50:51]
	v_mfma_f32_32x32x16_bf16 v[0:15], v[178:181], v[38:41], v[0:15]
	v_mfma_f32_32x32x16_bf16 v[0:15], v[182:185], v[190:193], v[0:15]
	s_waitcnt lgkmcnt(2)
	v_mfma_f32_32x32x16_bf16 v[16:31], v[120:123], v[198:201], v[16:31]
	v_lshrrev_b32_e32 v198, 3, v46
	v_xor_b32_e32 v198, v198, v47
	v_lshlrev_b32_e32 v198, 4, v198
	v_and_b32_e32 v42, 0xf0, v198
	v_add_u32_e32 v186, v35, v42
	ds_read_b128 v[42:45], v37 offset:52224
	ds_read_b128 v[186:189], v186
	v_bitop3_b32 v37, v46, v32, s23 bitop3:0x1e
	s_waitcnt lgkmcnt(3)
	v_mfma_f32_32x32x16_bf16 v[0:15], v[194:197], v[210:213], v[0:15]
	v_add_u32_e32 v46, 0x60, v36
	v_lshrrev_b32_e32 v38, 3, v46
	v_xor_b32_e32 v38, v38, v47
	v_lshlrev_b32_e32 v37, 1, v37
	v_lshlrev_b32_e32 v38, 4, v38
	v_and_b32_e32 v37, 0xf0, v37
	v_and_b32_e32 v38, 0xf0, v38
	s_waitcnt lgkmcnt(1)
	v_mfma_f32_32x32x16_bf16 v[0:15], v[214:217], v[42:45], v[0:15]
	v_add_u32_e32 v37, v207, v37
	v_add_u32_e32 v178, v35, v38
	ds_read_b128 v[38:41], v37 offset:52224
	ds_read_b128 v[178:181], v178
	v_bitop3_b32 v37, v46, v32, s23 bitop3:0x1e
	v_add_u32_e32 v46, 0x70, v36
	v_lshrrev_b32_e32 v182, 3, v46
	v_lshlrev_b32_e32 v37, 1, v37
	s_waitcnt lgkmcnt(1)
	v_mfma_f32_32x32x16_bf16 v[0:15], v[186:189], v[38:41], v[0:15]
	v_xor_b32_e32 v47, v182, v47
	v_and_b32_e32 v37, 0xf0, v37
	v_lshlrev_b32_e32 v47, 4, v47
	v_add_u32_e32 v37, v207, v37
	v_and_b32_e32 v47, 0xf0, v47
	v_add_u32_e32 v47, v35, v47
	ds_read_b128 v[182:185], v37 offset:52224
	ds_read_b128 v[190:193], v47
	s_waitcnt lgkmcnt(1)
	v_mfma_f32_32x32x16_bf16 v[0:15], v[178:181], v[182:185], v[0:15]
	v_bitop3_b32 v37, v46, v32, s23 bitop3:0x1e
	v_lshlrev_b32_e32 v37, 1, v37
	v_and_b32_e32 v37, 0xf0, v37
	v_add_u32_e32 v46, s7, v177
	v_add_u32_e32 v37, v207, v37
	ds_read_b128 v[42:45], v46 offset:1632
	ds_read_b128 v[38:41], v46 offset:1568
	ds_read_b128 v[186:189], v46 offset:1600
	ds_read_b128 v[194:197], v37 offset:52224
	ds_read_b128 v[198:201], v46 offset:1536
	s_waitcnt lgkmcnt(1)
	v_mfma_f32_32x32x16_bf16 v[0:15], v[190:193], v[194:197], v[0:15]
	v_mul_f32_e64 v30, v30, v44
	v_mul_f32_e64 v31, v31, v45
	v_mul_f32_e64 v28, v28, v42
	v_mul_f32_e64 v29, v29, v43
	v_mul_f32_e64 v26, v26, v188
	v_mul_f32_e64 v27, v27, v189
	v_pk_mul_f32 v[24:25], v[24:25], v[186:187]
	v_pk_mul_f32 v[22:23], v[22:23], v[40:41]
	v_pk_mul_f32 v[20:21], v[20:21], v[38:39]
	s_waitcnt lgkmcnt(0)
	v_pk_mul_f32 v[18:19], v[18:19], v[200:201]
	v_pk_mul_f32 v[16:17], v[16:17], v[198:199]
	s_cbranch_vccnz .LBB0_821
	v_lshl_add_u32 v37, v176, 2, s36
	ds_read_b32 v178, v37
	v_cndmask_b32_e64 v37, 0, 1, s[52:53]
	v_lshrrev_b32_e32 v181, 1, v33
	v_and_b32_e32 v33, 8, v36
	s_add_i32 s7, 0, 0x4400
	v_lshlrev_b32_e32 v37, 11, v37
	v_add_u32_e32 v182, v35, v33
	v_mov_b32_e32 v33, s7
	v_add_u32_e32 v179, 0, v37
	v_lshlrev_b32_e32 v180, 2, v34
	v_mad_u32_u24 v183, v32, s20, v33
	s_mov_b32 s7, s34
	v_add_u32_e32 v183, v183, v177
	v_add_u32_e32 v179, v179, v177
	v_add_u32_e32 v179, 0x22000, v179
	ds_read_b128 v[96:99], v183 offset:0
	ds_read_b128 v[100:103], v183 offset:32
	ds_read_b128 v[104:107], v183 offset:64
	ds_read_b128 v[108:111], v183 offset:96
